# seam direct release: last-arriving XCD leader bumps all 8 per-XCD generation flags itself (one poll hop fewer for non-leaders), leaders no longer bump their own
# baseline (speedup 1.0000x reference)
; __device__ __forceinline__ unsigned xb_ld(unsigned* p)              { return __hip_atomic_load(p, __ATOMIC_RELAXED, __HIP_MEMORY_SCOPE_AGENT); }
; __device__ __forceinline__ unsigned xb_add(unsigned* p, unsigned v) { return __hip_atomic_fetch_add(p, v, __ATOMIC_RELAXED, __HIP_MEMORY_SCOPE_AGENT); }
; #define XB_SPIN(cond, bar) do { unsigned _sp = 0; while (cond) { __builtin_amdgcn_s_sleep(1); \
;     if ((++_sp & 255u) == 0u) { if (xb_ld(&(bar)[XB_TMO])) break; if (_sp > XB_SPIN_CAP) { atomicAdd(&(bar)[XB_TMO], 1u); break; } } } } while (0)
; __device__ __forceinline__ void xcd_barrier(const XcdBarrier& b, const int wv) {
;     ...
;         const unsigned old = xb_add(&bar[XB_XSUB(b.x)], 1u);
;         const unsigned gen = old / nloc;
;         if (old + 1u == (gen + 1u) * nloc) {
;             __builtin_amdgcn_fence(__ATOMIC_RELEASE, "agent");
;             asm volatile("s_waitcnt vmcnt(0)" ::: "memory");
;             const unsigned og = xb_add(&bar[XB_TOP], 1u);
;             const unsigned tg = og / nx;
;             if (og + 1u == (tg + 1u) * nx) xb_add(&bar[XB_TOPGEN], 1u);
;             else XB_SPIN(xb_ld(&bar[XB_TOPGEN]) == tg, bar);
.Lseam1_345:
	s_or_b64 exec, exec, s[14:15]
	v_cvt_f32_u32_e32 v3, v0
	s_waitcnt vmcnt(0)
	v_readfirstlane_b32 s3, v2
	s_add_u32 s14, s6, 0x7500
	s_addc_u32 s15, s7, 0
	v_rcp_iflag_f32_e32 v3, v3
	v_add_u32_e32 v1, s3, v1
	v_add_u32_e32 v4, 1, v1
	s_mov_b64 s[16:17], -1
	v_mul_f32_e32 v2, 0x4f7ffffe, v3
	v_cvt_u32_f32_e32 v2, v2
	v_sub_u32_e32 v3, 0, v0
	v_mul_lo_u32 v3, v3, v2
	v_mul_hi_u32 v3, v2, v3
	v_add_u32_e32 v2, v2, v3
	v_mul_hi_u32 v2, v1, v2
	v_mul_lo_u32 v3, v2, v0
	v_sub_u32_e32 v1, v1, v3
	v_add_u32_e32 v5, 1, v2
	v_cmp_ge_u32_e32 vcc, v1, v0
	v_sub_u32_e32 v3, v1, v0
	s_nop 0
	v_cndmask_b32_e32 v2, v2, v5, vcc
	v_cndmask_b32_e32 v1, v1, v3, vcc
	v_add_u32_e32 v3, 1, v2
	v_cmp_ge_u32_e32 vcc, v1, v0
	s_nop 1
	v_cndmask_b32_e32 v2, v2, v3, vcc
	v_mul_lo_u32 v1, v0, v2
	v_add_u32_e32 v0, v1, v0
	v_cmp_ne_u32_e32 vcc, v4, v0
	v_mov_b64_e32 v[0:1], s[14:15]
	s_cbranch_vccnz .Ldr_0
	s_add_u32 s12, s6, 0x63ff
	s_addc_u32 s13, s7, 0
	v_mov_b32_e32 v19, 1
	global_atomic_add v19, v19, s[12:13]
	global_atomic_add v19, v19, s[12:13] offset:256
	global_atomic_add v19, v19, s[12:13] offset:512
	global_atomic_add v19, v19, s[12:13] offset:768
	global_atomic_add v19, v19, s[12:13] offset:1024
	global_atomic_add v19, v19, s[12:13] offset:1280
	global_atomic_add v19, v19, s[12:13] offset:1536
	global_atomic_add v19, v19, s[12:13] offset:1792
.Ldr_0:
	s_and_saveexec_b64 s[12:13], vcc
	s_cbranch_execz .Lseam1_357
	v_mov_b32_e32 v0, 0
	global_load_dword v1, v0, s[14:15] sc1
	s_mov_b64 s[20:21], 0
	s_waitcnt vmcnt(0)
	v_cmp_eq_u32_e32 vcc, v1, v2
	s_and_saveexec_b64 s[18:19], vcc
	s_cbranch_execz .Lseam1_356
	s_add_u32 s16, s6, 0x4200
	s_addc_u32 s17, s7, 0
	s_mov_b32 s3, 1
	s_mov_b64 s[6:7], 0
	s_branch .Lseam1_349

; __device__ __forceinline__ unsigned xb_add(unsigned* p, unsigned v) { return __hip_atomic_fetch_add(p, v, __ATOMIC_RELAXED, __HIP_MEMORY_SCOPE_AGENT); }
; __device__ __forceinline__ void xcd_barrier(const XcdBarrier& b, const int wv) {
;     ...
;             __builtin_amdgcn_fence(__ATOMIC_ACQUIRE, "agent");
;             xb_add(&bar[XB_XGEN(b.x)], 1u);
;             asm volatile("s_waitcnt vmcnt(0)" ::: "memory");
.Lseam1_359:
	s_or_b64 exec, exec, s[6:7]
	s_mov_b64 s[6:7], exec
	v_mbcnt_lo_u32_b32 v0, s6, 0
	v_mbcnt_hi_u32_b32 v0, s7, v0
	v_cmp_eq_u32_e32 vcc, 0, v0
	s_waitcnt vmcnt(0)
	buffer_inv sc1
	s_and_saveexec_b64 s[12:13], vcc
	s_cbranch_execz .Lseam1_361
	s_bcnt1_i32_b64 s3, s[6:7]
	v_mov_b32_e32 v0, 0x2000
	v_mov_b32_e32 v1, s3
.Lseam1_361:
	s_or_b64 exec, exec, s[12:13]
	s_waitcnt vmcnt(0)

; __device__ __forceinline__ unsigned xb_add(unsigned* p, unsigned v) { return __hip_atomic_fetch_add(p, v, __ATOMIC_RELAXED, __HIP_MEMORY_SCOPE_AGENT); }
; __device__ __forceinline__ void xcd_barrier(const XcdBarrier& b, const int wv) {
;     ...
;             __builtin_amdgcn_fence(__ATOMIC_ACQUIRE, "agent");
;             xb_add(&bar[XB_XGEN(b.x)], 1u);
;             asm volatile("s_waitcnt vmcnt(0)" ::: "memory");
.LBB0_359:
	s_or_b64 exec, exec, s[6:7]
	s_mov_b64 s[6:7], exec
	v_mbcnt_lo_u32_b32 v0, s6, 0
	v_mbcnt_hi_u32_b32 v0, s7, v0
	v_cmp_eq_u32_e32 vcc, 0, v0
	s_waitcnt vmcnt(0)
	buffer_inv sc1
	s_and_saveexec_b64 s[12:13], vcc
	s_cbranch_execz .LBB0_361
	s_bcnt1_i32_b64 s3, s[6:7]
	v_mov_b32_e32 v0, 0x2000
	v_mov_b32_e32 v1, s3
.LBB0_361:
	s_or_b64 exec, exec, s[12:13]
	s_waitcnt vmcnt(0)

; __device__ __forceinline__ unsigned xb_add(unsigned* p, unsigned v) { return __hip_atomic_fetch_add(p, v, __ATOMIC_RELAXED, __HIP_MEMORY_SCOPE_AGENT); }
; __device__ __forceinline__ void xcd_barrier(const XcdBarrier& b, const int wv) {
;     ...
;             __builtin_amdgcn_fence(__ATOMIC_ACQUIRE, "agent");
;             xb_add(&bar[XB_XGEN(b.x)], 1u);
;             asm volatile("s_waitcnt vmcnt(0)" ::: "memory");
.LBB0_593:
	s_or_b64 exec, exec, s[6:7]
	s_mov_b64 s[6:7], exec
	v_mbcnt_lo_u32_b32 v0, s6, 0
	v_mbcnt_hi_u32_b32 v0, s7, v0
	v_cmp_eq_u32_e32 vcc, 0, v0
	s_waitcnt vmcnt(0)
	buffer_inv sc1
	s_and_saveexec_b64 s[12:13], vcc
	s_cbranch_execz .LBB0_595
	s_bcnt1_i32_b64 s3, s[6:7]
	v_mov_b32_e32 v0, 0x2000
	v_mov_b32_e32 v1, s3
.LBB0_595:
	s_or_b64 exec, exec, s[12:13]
	s_waitcnt vmcnt(0)

; __device__ __forceinline__ unsigned xb_add(unsigned* p, unsigned v) { return __hip_atomic_fetch_add(p, v, __ATOMIC_RELAXED, __HIP_MEMORY_SCOPE_AGENT); }
; __device__ __forceinline__ void xcd_barrier(const XcdBarrier& b, const int wv) {
;     ...
;             __builtin_amdgcn_fence(__ATOMIC_ACQUIRE, "agent");
;             xb_add(&bar[XB_XGEN(b.x)], 1u);
;             asm volatile("s_waitcnt vmcnt(0)" ::: "memory");
.LBB0_648:
	s_or_b64 exec, exec, s[6:7]
	s_mov_b64 s[6:7], exec
	v_mbcnt_lo_u32_b32 v0, s6, 0
	v_mbcnt_hi_u32_b32 v0, s7, v0
	v_cmp_eq_u32_e32 vcc, 0, v0
	s_waitcnt vmcnt(0)
	buffer_inv sc1
	s_and_saveexec_b64 s[12:13], vcc
	s_cbranch_execz .LBB0_650
	s_bcnt1_i32_b64 s3, s[6:7]
	v_mov_b32_e32 v0, 0x2000
	v_mov_b32_e32 v1, s3
.LBB0_650:
	s_or_b64 exec, exec, s[12:13]
	s_waitcnt vmcnt(0)

; __device__ __forceinline__ unsigned xb_ld(unsigned* p)              { return __hip_atomic_load(p, __ATOMIC_RELAXED, __HIP_MEMORY_SCOPE_AGENT); }
; __device__ __forceinline__ unsigned xb_add(unsigned* p, unsigned v) { return __hip_atomic_fetch_add(p, v, __ATOMIC_RELAXED, __HIP_MEMORY_SCOPE_AGENT); }
; #define XB_SPIN(cond, bar) do { unsigned _sp = 0; while (cond) { __builtin_amdgcn_s_sleep(1); \
;     if ((++_sp & 255u) == 0u) { if (xb_ld(&(bar)[XB_TMO])) break; if (_sp > XB_SPIN_CAP) { atomicAdd(&(bar)[XB_TMO], 1u); break; } } } } while (0)
; __device__ __forceinline__ void xcd_barrier(const XcdBarrier& b, const int wv) {
;     ...
;         const unsigned old = xb_add(&bar[XB_XSUB(b.x)], 1u);
;         const unsigned gen = old / nloc;
;         if (old + 1u == (gen + 1u) * nloc) {
;             __builtin_amdgcn_fence(__ATOMIC_RELEASE, "agent");
;             asm volatile("s_waitcnt vmcnt(0)" ::: "memory");
;             const unsigned og = xb_add(&bar[XB_TOP], 1u);
;             const unsigned tg = og / nx;
;             if (og + 1u == (tg + 1u) * nx) xb_add(&bar[XB_TOPGEN], 1u);
;             else XB_SPIN(xb_ld(&bar[XB_TOPGEN]) == tg, bar);
.LBB0_744:
	s_or_b64 exec, exec, s[16:17]
	v_cvt_f32_u32_e32 v3, v0
	s_waitcnt vmcnt(0)
	v_readfirstlane_b32 s3, v2
	s_add_u32 s16, s10, 0x7500
	s_addc_u32 s17, s11, 0
	v_rcp_iflag_f32_e32 v3, v3
	v_add_u32_e32 v1, s3, v1
	v_add_u32_e32 v4, 1, v1
	s_mov_b64 s[18:19], -1
	v_mul_f32_e32 v2, 0x4f7ffffe, v3
	v_cvt_u32_f32_e32 v2, v2
	v_sub_u32_e32 v3, 0, v0
	v_mul_lo_u32 v3, v3, v2
	v_mul_hi_u32 v3, v2, v3
	v_add_u32_e32 v2, v2, v3
	v_mul_hi_u32 v2, v1, v2
	v_mul_lo_u32 v3, v2, v0
	v_sub_u32_e32 v1, v1, v3
	v_add_u32_e32 v5, 1, v2
	v_cmp_ge_u32_e32 vcc, v1, v0
	v_sub_u32_e32 v3, v1, v0
	s_nop 0
	v_cndmask_b32_e32 v2, v2, v5, vcc
	v_cndmask_b32_e32 v1, v1, v3, vcc
	v_add_u32_e32 v3, 1, v2
	v_cmp_ge_u32_e32 vcc, v1, v0
	s_nop 1
	v_cndmask_b32_e32 v2, v2, v3, vcc
	v_mul_lo_u32 v1, v0, v2
	v_add_u32_e32 v0, v1, v0
	v_cmp_ne_u32_e32 vcc, v4, v0
	v_mov_b64_e32 v[0:1], s[16:17]
	s_cbranch_vccnz .Ldr_4
	s_add_u32 s14, s10, 0x63ff
	s_addc_u32 s15, s11, 0
	v_mov_b32_e32 v19, 1
	global_atomic_add v19, v19, s[14:15]
	global_atomic_add v19, v19, s[14:15] offset:256
	global_atomic_add v19, v19, s[14:15] offset:512
	global_atomic_add v19, v19, s[14:15] offset:768
	global_atomic_add v19, v19, s[14:15] offset:1024
	global_atomic_add v19, v19, s[14:15] offset:1280
	global_atomic_add v19, v19, s[14:15] offset:1536
	global_atomic_add v19, v19, s[14:15] offset:1792
.Ldr_4:
	s_and_saveexec_b64 s[14:15], vcc
	s_cbranch_execz .LBB0_756
	v_mov_b32_e32 v0, 0
	global_load_dword v1, v0, s[16:17] sc1
	s_mov_b64 s[22:23], 0
	s_waitcnt vmcnt(0)
	v_cmp_eq_u32_e32 vcc, v1, v2
	s_and_saveexec_b64 s[20:21], vcc
	s_cbranch_execz .LBB0_755
	s_add_u32 s18, s10, 0x4200
	s_addc_u32 s19, s11, 0
	s_mov_b32 s3, 1
	s_mov_b64 s[10:11], 0
	s_branch .LBB0_748

; __device__ __forceinline__ unsigned xb_add(unsigned* p, unsigned v) { return __hip_atomic_fetch_add(p, v, __ATOMIC_RELAXED, __HIP_MEMORY_SCOPE_AGENT); }
; __device__ __forceinline__ void xcd_barrier(const XcdBarrier& b, const int wv) {
;     ...
;             __builtin_amdgcn_fence(__ATOMIC_ACQUIRE, "agent");
;             xb_add(&bar[XB_XGEN(b.x)], 1u);
;             asm volatile("s_waitcnt vmcnt(0)" ::: "memory");
.LBB0_758:
	s_or_b64 exec, exec, s[10:11]
	s_mov_b64 s[10:11], exec
	v_mbcnt_lo_u32_b32 v0, s10, 0
	v_mbcnt_hi_u32_b32 v0, s11, v0
	v_cmp_eq_u32_e32 vcc, 0, v0
	s_waitcnt vmcnt(0)
	buffer_inv sc1
	s_and_saveexec_b64 s[14:15], vcc
	s_cbranch_execz .LBB0_760
	s_bcnt1_i32_b64 s3, s[10:11]
	v_mov_b32_e32 v0, 0x2000
	v_mov_b32_e32 v1, s3
.LBB0_760:
	s_or_b64 exec, exec, s[14:15]
	s_waitcnt vmcnt(0)

; __device__ __forceinline__ unsigned xb_add(unsigned* p, unsigned v) { return __hip_atomic_fetch_add(p, v, __ATOMIC_RELAXED, __HIP_MEMORY_SCOPE_AGENT); }
; __device__ __forceinline__ void xcd_barrier(const XcdBarrier& b, const int wv) {
;     ...
;             __builtin_amdgcn_fence(__ATOMIC_ACQUIRE, "agent");
;             xb_add(&bar[XB_XGEN(b.x)], 1u);
;             asm volatile("s_waitcnt vmcnt(0)" ::: "memory");
.LBB0_834:
	s_or_b64 exec, exec, s[10:11]
	s_mov_b64 s[10:11], exec
	v_mbcnt_lo_u32_b32 v0, s10, 0
	v_mbcnt_hi_u32_b32 v0, s11, v0
	v_cmp_eq_u32_e32 vcc, 0, v0
	s_waitcnt vmcnt(0)
	buffer_inv sc1
	s_and_saveexec_b64 s[14:15], vcc
	s_cbranch_execz .LBB0_836
	s_bcnt1_i32_b64 s3, s[10:11]
	v_mov_b32_e32 v0, 0x2000
	v_mov_b32_e32 v1, s3
.LBB0_836:
	s_or_b64 exec, exec, s[14:15]
	s_waitcnt vmcnt(0)

; __device__ __forceinline__ unsigned xb_ld(unsigned* p)              { return __hip_atomic_load(p, __ATOMIC_RELAXED, __HIP_MEMORY_SCOPE_AGENT); }
; __device__ __forceinline__ unsigned xb_add(unsigned* p, unsigned v) { return __hip_atomic_fetch_add(p, v, __ATOMIC_RELAXED, __HIP_MEMORY_SCOPE_AGENT); }
; #define XB_SPIN(cond, bar) do { unsigned _sp = 0; while (cond) { __builtin_amdgcn_s_sleep(1); \
;     if ((++_sp & 255u) == 0u) { if (xb_ld(&(bar)[XB_TMO])) break; if (_sp > XB_SPIN_CAP) { atomicAdd(&(bar)[XB_TMO], 1u); break; } } } } while (0)
; __device__ __forceinline__ void xcd_barrier(const XcdBarrier& b, const int wv) {
;     ...
;         const unsigned old = xb_add(&bar[XB_XSUB(b.x)], 1u);
;         const unsigned gen = old / nloc;
;         if (old + 1u == (gen + 1u) * nloc) {
;             __builtin_amdgcn_fence(__ATOMIC_RELEASE, "agent");
;             asm volatile("s_waitcnt vmcnt(0)" ::: "memory");
;             const unsigned og = xb_add(&bar[XB_TOP], 1u);
;             const unsigned tg = og / nx;
;             if (og + 1u == (tg + 1u) * nx) xb_add(&bar[XB_TOPGEN], 1u);
;             else XB_SPIN(xb_ld(&bar[XB_TOPGEN]) == tg, bar);
.LBB0_877:
	s_or_b64 exec, exec, s[18:19]
	v_cvt_f32_u32_e32 v3, v0
	s_waitcnt vmcnt(0)
	v_readfirstlane_b32 s3, v2
	s_add_u32 s18, s12, 0x7500
	s_addc_u32 s19, s13, 0
	v_rcp_iflag_f32_e32 v3, v3
	v_add_u32_e32 v1, s3, v1
	v_add_u32_e32 v4, 1, v1
	s_mov_b64 s[20:21], -1
	v_mul_f32_e32 v2, 0x4f7ffffe, v3
	v_cvt_u32_f32_e32 v2, v2
	v_sub_u32_e32 v3, 0, v0
	v_mul_lo_u32 v3, v3, v2
	v_mul_hi_u32 v3, v2, v3
	v_add_u32_e32 v2, v2, v3
	v_mul_hi_u32 v2, v1, v2
	v_mul_lo_u32 v3, v2, v0
	v_sub_u32_e32 v1, v1, v3
	v_add_u32_e32 v5, 1, v2
	v_cmp_ge_u32_e32 vcc, v1, v0
	v_sub_u32_e32 v3, v1, v0
	s_nop 0
	v_cndmask_b32_e32 v2, v2, v5, vcc
	v_cndmask_b32_e32 v1, v1, v3, vcc
	v_add_u32_e32 v3, 1, v2
	v_cmp_ge_u32_e32 vcc, v1, v0
	s_nop 1
	v_cndmask_b32_e32 v2, v2, v3, vcc
	v_mul_lo_u32 v1, v0, v2
	v_add_u32_e32 v0, v1, v0
	v_cmp_ne_u32_e32 vcc, v4, v0
	v_mov_b64_e32 v[0:1], s[18:19]
	s_cbranch_vccnz .Ldr_6
	s_add_u32 s16, s12, 0x63ff
	s_addc_u32 s17, s13, 0
	v_mov_b32_e32 v19, 1
	global_atomic_add v19, v19, s[16:17]
	global_atomic_add v19, v19, s[16:17] offset:256
	global_atomic_add v19, v19, s[16:17] offset:512
	global_atomic_add v19, v19, s[16:17] offset:768
	global_atomic_add v19, v19, s[16:17] offset:1024
	global_atomic_add v19, v19, s[16:17] offset:1280
	global_atomic_add v19, v19, s[16:17] offset:1536
	global_atomic_add v19, v19, s[16:17] offset:1792
.Ldr_6:
	s_and_saveexec_b64 s[16:17], vcc
	s_cbranch_execz .LBB0_889
	v_mov_b32_e32 v0, 0
	global_load_dword v1, v0, s[18:19] sc1
	s_mov_b64 s[24:25], 0
	s_waitcnt vmcnt(0)
	v_cmp_eq_u32_e32 vcc, v1, v2
	s_and_saveexec_b64 s[22:23], vcc
	s_cbranch_execz .LBB0_888
	s_add_u32 s20, s12, 0x4200
	s_addc_u32 s21, s13, 0
	s_mov_b32 s3, 1
	s_mov_b64 s[12:13], 0
	s_branch .LBB0_881

; __device__ __forceinline__ unsigned xb_add(unsigned* p, unsigned v) { return __hip_atomic_fetch_add(p, v, __ATOMIC_RELAXED, __HIP_MEMORY_SCOPE_AGENT); }
; __device__ __forceinline__ void xcd_barrier(const XcdBarrier& b, const int wv) {
;     ...
;             __builtin_amdgcn_fence(__ATOMIC_ACQUIRE, "agent");
;             xb_add(&bar[XB_XGEN(b.x)], 1u);
;             asm volatile("s_waitcnt vmcnt(0)" ::: "memory");
.LBB0_891:
	s_or_b64 exec, exec, s[12:13]
	s_mov_b64 s[12:13], exec
	v_mbcnt_lo_u32_b32 v0, s12, 0
	v_mbcnt_hi_u32_b32 v0, s13, v0
	v_cmp_eq_u32_e32 vcc, 0, v0
	s_waitcnt vmcnt(0)
	buffer_inv sc1
	s_and_saveexec_b64 s[16:17], vcc
	s_cbranch_execz .LBB0_893
	s_bcnt1_i32_b64 s3, s[12:13]
	v_mov_b32_e32 v0, 0x2000
	v_mov_b32_e32 v1, s3
.LBB0_893:
	s_or_b64 exec, exec, s[16:17]
	s_waitcnt vmcnt(0)

; __device__ __forceinline__ unsigned xb_add(unsigned* p, unsigned v) { return __hip_atomic_fetch_add(p, v, __ATOMIC_RELAXED, __HIP_MEMORY_SCOPE_AGENT); }
; __device__ __forceinline__ void xcd_barrier(const XcdBarrier& b, const int wv) {
;     ...
;             __builtin_amdgcn_fence(__ATOMIC_ACQUIRE, "agent");
;             xb_add(&bar[XB_XGEN(b.x)], 1u);
;             asm volatile("s_waitcnt vmcnt(0)" ::: "memory");
.LBB0_959:
	s_or_b64 exec, exec, s[12:13]
	s_mov_b64 s[12:13], exec
	v_mbcnt_lo_u32_b32 v0, s12, 0
	v_mbcnt_hi_u32_b32 v0, s13, v0
	v_cmp_eq_u32_e32 vcc, 0, v0
	s_waitcnt vmcnt(0)
	buffer_inv sc1
	s_and_saveexec_b64 s[16:17], vcc
	s_cbranch_execz .LBB0_961
	s_bcnt1_i32_b64 s3, s[12:13]
	v_mov_b32_e32 v0, 0x2000
	v_mov_b32_e32 v1, s3
.LBB0_961:
	s_or_b64 exec, exec, s[16:17]
	s_waitcnt vmcnt(0)

; __device__ __forceinline__ unsigned xb_add(unsigned* p, unsigned v) { return __hip_atomic_fetch_add(p, v, __ATOMIC_RELAXED, __HIP_MEMORY_SCOPE_AGENT); }
; __device__ __forceinline__ void xcd_barrier(const XcdBarrier& b, const int wv) {
;     ...
;             __builtin_amdgcn_fence(__ATOMIC_ACQUIRE, "agent");
;             xb_add(&bar[XB_XGEN(b.x)], 1u);
;             asm volatile("s_waitcnt vmcnt(0)" ::: "memory");
.LBB0_1036:
	s_or_b64 exec, exec, s[12:13]
	s_mov_b64 s[12:13], exec
	v_mbcnt_lo_u32_b32 v0, s12, 0
	v_mbcnt_hi_u32_b32 v0, s13, v0
	v_cmp_eq_u32_e32 vcc, 0, v0
	s_waitcnt vmcnt(0)
	buffer_inv sc1
	s_and_saveexec_b64 s[16:17], vcc
	s_cbranch_execz .LBB0_1038
	s_bcnt1_i32_b64 s3, s[12:13]
	v_mov_b32_e32 v0, 0x2000
	v_mov_b32_e32 v1, s3
.LBB0_1038:
	s_or_b64 exec, exec, s[16:17]
	s_waitcnt vmcnt(0)

; __device__ __forceinline__ unsigned xb_add(unsigned* p, unsigned v) { return __hip_atomic_fetch_add(p, v, __ATOMIC_RELAXED, __HIP_MEMORY_SCOPE_AGENT); }
; __device__ __forceinline__ void xcd_barrier(const XcdBarrier& b, const int wv) {
;     ...
;             __builtin_amdgcn_fence(__ATOMIC_ACQUIRE, "agent");
;             xb_add(&bar[XB_XGEN(b.x)], 1u);
;             asm volatile("s_waitcnt vmcnt(0)" ::: "memory");
.LBB0_1113:
	s_or_b64 exec, exec, s[12:13]
	s_mov_b64 s[12:13], exec
	v_mbcnt_lo_u32_b32 v0, s12, 0
	v_mbcnt_hi_u32_b32 v0, s13, v0
	v_cmp_eq_u32_e32 vcc, 0, v0
	s_waitcnt vmcnt(0)
	buffer_inv sc1
	s_and_saveexec_b64 s[16:17], vcc
	s_cbranch_execz .LBB0_1115
	s_bcnt1_i32_b64 s3, s[12:13]
	v_mov_b32_e32 v0, 0x2000
	v_mov_b32_e32 v1, s3
.LBB0_1115:
	s_or_b64 exec, exec, s[16:17]
	s_waitcnt vmcnt(0)

; __device__ __forceinline__ unsigned xb_add(unsigned* p, unsigned v) { return __hip_atomic_fetch_add(p, v, __ATOMIC_RELAXED, __HIP_MEMORY_SCOPE_AGENT); }
; __device__ __forceinline__ void xcd_barrier(const XcdBarrier& b, const int wv) {
;     ...
;             __builtin_amdgcn_fence(__ATOMIC_ACQUIRE, "agent");
;             xb_add(&bar[XB_XGEN(b.x)], 1u);
;             asm volatile("s_waitcnt vmcnt(0)" ::: "memory");
.LBB0_1399:
	s_or_b64 exec, exec, s[10:11]
	s_mov_b64 s[10:11], exec
	v_mbcnt_lo_u32_b32 v0, s10, 0
	v_mbcnt_hi_u32_b32 v0, s11, v0
	v_cmp_eq_u32_e32 vcc, 0, v0
	s_waitcnt vmcnt(0)
	buffer_inv sc1
	s_and_saveexec_b64 s[14:15], vcc
	s_cbranch_execz .LBB0_1401
	s_bcnt1_i32_b64 s3, s[10:11]
	v_mov_b32_e32 v0, 0x2000
	v_mov_b32_e32 v1, s3
.LBB0_1401:
	s_or_b64 exec, exec, s[14:15]
	s_waitcnt vmcnt(0)

; __device__ __forceinline__ unsigned xb_add(unsigned* p, unsigned v) { return __hip_atomic_fetch_add(p, v, __ATOMIC_RELAXED, __HIP_MEMORY_SCOPE_AGENT); }
; __device__ __forceinline__ void xcd_barrier(const XcdBarrier& b, const int wv) {
;     ...
;             __builtin_amdgcn_fence(__ATOMIC_ACQUIRE, "agent");
;             xb_add(&bar[XB_XGEN(b.x)], 1u);
;             asm volatile("s_waitcnt vmcnt(0)" ::: "memory");
.LBB0_1633:
	s_or_b64 exec, exec, s[10:11]
	s_mov_b64 s[10:11], exec
	v_mbcnt_lo_u32_b32 v0, s10, 0
	v_mbcnt_hi_u32_b32 v0, s11, v0
	v_cmp_eq_u32_e32 vcc, 0, v0
	s_waitcnt vmcnt(0)
	buffer_inv sc1
	s_and_saveexec_b64 s[14:15], vcc
	s_cbranch_execz .LBB0_1635
	s_bcnt1_i32_b64 s3, s[10:11]
	v_mov_b32_e32 v0, 0x2000
	v_mov_b32_e32 v1, s3
.LBB0_1635:
	s_or_b64 exec, exec, s[14:15]
	s_waitcnt vmcnt(0)

; __device__ __forceinline__ unsigned xb_add(unsigned* p, unsigned v) { return __hip_atomic_fetch_add(p, v, __ATOMIC_RELAXED, __HIP_MEMORY_SCOPE_AGENT); }
; __device__ __forceinline__ void xcd_barrier(const XcdBarrier& b, const int wv) {
;     ...
;             __builtin_amdgcn_fence(__ATOMIC_ACQUIRE, "agent");
;             xb_add(&bar[XB_XGEN(b.x)], 1u);
;             asm volatile("s_waitcnt vmcnt(0)" ::: "memory");
.LBB0_1688:
	s_or_b64 exec, exec, s[10:11]
	s_mov_b64 s[10:11], exec
	v_mbcnt_lo_u32_b32 v0, s10, 0
	v_mbcnt_hi_u32_b32 v0, s11, v0
	v_cmp_eq_u32_e32 vcc, 0, v0
	s_waitcnt vmcnt(0)
	buffer_inv sc1
	s_and_saveexec_b64 s[14:15], vcc
	s_cbranch_execz .LBB0_1690
	s_bcnt1_i32_b64 s3, s[10:11]
	v_mov_b32_e32 v0, 0x2000
	v_mov_b32_e32 v1, s3
.LBB0_1690:
	s_or_b64 exec, exec, s[14:15]
	s_waitcnt vmcnt(0)

; __device__ __forceinline__ unsigned xb_add(unsigned* p, unsigned v) { return __hip_atomic_fetch_add(p, v, __ATOMIC_RELAXED, __HIP_MEMORY_SCOPE_AGENT); }
; __device__ __forceinline__ void xcd_barrier(const XcdBarrier& b, const int wv) {
;     ...
;             __builtin_amdgcn_fence(__ATOMIC_ACQUIRE, "agent");
;             xb_add(&bar[XB_XGEN(b.x)], 1u);
;             asm volatile("s_waitcnt vmcnt(0)" ::: "memory");
.LBB0_1798:
	s_or_b64 exec, exec, s[10:11]
	s_mov_b64 s[10:11], exec
	v_mbcnt_lo_u32_b32 v0, s10, 0
	v_mbcnt_hi_u32_b32 v0, s11, v0
	v_cmp_eq_u32_e32 vcc, 0, v0
	s_waitcnt vmcnt(0)
	buffer_inv sc1
	s_and_saveexec_b64 s[14:15], vcc
	s_cbranch_execz .LBB0_1800
	s_bcnt1_i32_b64 s3, s[10:11]
	v_mov_b32_e32 v0, 0x2000
	v_mov_b32_e32 v1, s3
.LBB0_1800:
	s_or_b64 exec, exec, s[14:15]
	s_waitcnt vmcnt(0)

; __device__ __forceinline__ unsigned xb_add(unsigned* p, unsigned v) { return __hip_atomic_fetch_add(p, v, __ATOMIC_RELAXED, __HIP_MEMORY_SCOPE_AGENT); }
; __device__ __forceinline__ void xcd_barrier(const XcdBarrier& b, const int wv) {
;     ...
;             __builtin_amdgcn_fence(__ATOMIC_ACQUIRE, "agent");
;             xb_add(&bar[XB_XGEN(b.x)], 1u);
;             asm volatile("s_waitcnt vmcnt(0)" ::: "memory");
.LBB0_1875:
	s_or_b64 exec, exec, s[10:11]
	s_mov_b64 s[10:11], exec
	v_mbcnt_lo_u32_b32 v0, s10, 0
	v_mbcnt_hi_u32_b32 v0, s11, v0
	v_cmp_eq_u32_e32 vcc, 0, v0
	s_waitcnt vmcnt(0)
	buffer_inv sc1
	s_and_saveexec_b64 s[14:15], vcc
	s_cbranch_execz .LBB0_1877
	s_bcnt1_i32_b64 s3, s[10:11]
	v_mov_b32_e32 v0, 0x2000
	v_mov_b32_e32 v1, s3
.LBB0_1877:
	s_or_b64 exec, exec, s[14:15]
	s_waitcnt vmcnt(0)

; __device__ __forceinline__ unsigned xb_add(unsigned* p, unsigned v) { return __hip_atomic_fetch_add(p, v, __ATOMIC_RELAXED, __HIP_MEMORY_SCOPE_AGENT); }
; __device__ __forceinline__ void xcd_barrier(const XcdBarrier& b, const int wv) {
;     ...
;             __builtin_amdgcn_fence(__ATOMIC_ACQUIRE, "agent");
;             xb_add(&bar[XB_XGEN(b.x)], 1u);
;             asm volatile("s_waitcnt vmcnt(0)" ::: "memory");
.LBB0_1951:
	s_or_b64 exec, exec, s[10:11]
	s_mov_b64 s[10:11], exec
	v_mbcnt_lo_u32_b32 v0, s10, 0
	v_mbcnt_hi_u32_b32 v0, s11, v0
	v_cmp_eq_u32_e32 vcc, 0, v0
	s_waitcnt vmcnt(0)
	buffer_inv sc1
	s_and_saveexec_b64 s[14:15], vcc
	s_cbranch_execz .LBB0_1953
	s_bcnt1_i32_b64 s3, s[10:11]
	v_mov_b32_e32 v0, 0x2000
	v_mov_b32_e32 v1, s3
.LBB0_1953:
	s_or_b64 exec, exec, s[14:15]
	s_waitcnt vmcnt(0)

; __device__ __forceinline__ unsigned xb_ld(unsigned* p)              { return __hip_atomic_load(p, __ATOMIC_RELAXED, __HIP_MEMORY_SCOPE_AGENT); }
; __device__ __forceinline__ unsigned xb_add(unsigned* p, unsigned v) { return __hip_atomic_fetch_add(p, v, __ATOMIC_RELAXED, __HIP_MEMORY_SCOPE_AGENT); }
; #define XB_SPIN(cond, bar) do { unsigned _sp = 0; while (cond) { __builtin_amdgcn_s_sleep(1); \
;     if ((++_sp & 255u) == 0u) { if (xb_ld(&(bar)[XB_TMO])) break; if (_sp > XB_SPIN_CAP) { atomicAdd(&(bar)[XB_TMO], 1u); break; } } } } while (0)
; __device__ __forceinline__ void xcd_barrier(const XcdBarrier& b, const int wv) {
;     ...
;         const unsigned old = xb_add(&bar[XB_XSUB(b.x)], 1u);
;         const unsigned gen = old / nloc;
;         if (old + 1u == (gen + 1u) * nloc) {
;             __builtin_amdgcn_fence(__ATOMIC_RELEASE, "agent");
;             asm volatile("s_waitcnt vmcnt(0)" ::: "memory");
;             const unsigned og = xb_add(&bar[XB_TOP], 1u);
;             const unsigned tg = og / nx;
;             if (og + 1u == (tg + 1u) * nx) xb_add(&bar[XB_TOPGEN], 1u);
;             else XB_SPIN(xb_ld(&bar[XB_TOPGEN]) == tg, bar);
.LBB0_2064:
	s_or_b64 exec, exec, s[16:17]
	v_cvt_f32_u32_e32 v3, v0
	s_waitcnt vmcnt(0)
	v_readfirstlane_b32 s3, v2
	s_add_u32 s16, s8, 0x7500
	s_addc_u32 s17, s9, 0
	v_rcp_iflag_f32_e32 v3, v3
	v_add_u32_e32 v1, s3, v1
	v_add_u32_e32 v4, 1, v1
	s_mov_b64 s[18:19], -1
	v_mul_f32_e32 v2, 0x4f7ffffe, v3
	v_cvt_u32_f32_e32 v2, v2
	v_sub_u32_e32 v3, 0, v0
	v_mul_lo_u32 v3, v3, v2
	v_mul_hi_u32 v3, v2, v3
	v_add_u32_e32 v2, v2, v3
	v_mul_hi_u32 v2, v1, v2
	v_mul_lo_u32 v3, v2, v0
	v_sub_u32_e32 v1, v1, v3
	v_add_u32_e32 v5, 1, v2
	v_cmp_ge_u32_e32 vcc, v1, v0
	v_sub_u32_e32 v3, v1, v0
	s_nop 0
	v_cndmask_b32_e32 v2, v2, v5, vcc
	v_cndmask_b32_e32 v1, v1, v3, vcc
	v_add_u32_e32 v3, 1, v2
	v_cmp_ge_u32_e32 vcc, v1, v0
	s_nop 1
	v_cndmask_b32_e32 v2, v2, v3, vcc
	v_mul_lo_u32 v1, v0, v2
	v_add_u32_e32 v0, v1, v0
	v_cmp_ne_u32_e32 vcc, v4, v0
	v_mov_b64_e32 v[0:1], s[16:17]
	s_cbranch_vccnz .Ldr_16
	s_add_u32 s14, s8, 0x63ff
	s_addc_u32 s15, s9, 0
	v_mov_b32_e32 v19, 1
	global_atomic_add v19, v19, s[14:15]
	global_atomic_add v19, v19, s[14:15] offset:256
	global_atomic_add v19, v19, s[14:15] offset:512
	global_atomic_add v19, v19, s[14:15] offset:768
	global_atomic_add v19, v19, s[14:15] offset:1024
	global_atomic_add v19, v19, s[14:15] offset:1280
	global_atomic_add v19, v19, s[14:15] offset:1536
	global_atomic_add v19, v19, s[14:15] offset:1792
.Ldr_16:
	s_and_saveexec_b64 s[14:15], vcc
	s_cbranch_execz .LBB0_2076
	v_mov_b32_e32 v0, 0
	global_load_dword v1, v0, s[16:17] sc1
	s_mov_b64 s[22:23], 0
	s_waitcnt vmcnt(0)
	v_cmp_eq_u32_e32 vcc, v1, v2
	s_and_saveexec_b64 s[20:21], vcc
	s_cbranch_execz .LBB0_2075
	s_add_u32 s18, s8, 0x4200
	s_addc_u32 s19, s9, 0
	s_mov_b32 s3, 1
	s_mov_b64 s[8:9], 0
	s_branch .LBB0_2068

; __device__ __forceinline__ unsigned xb_add(unsigned* p, unsigned v) { return __hip_atomic_fetch_add(p, v, __ATOMIC_RELAXED, __HIP_MEMORY_SCOPE_AGENT); }
; __device__ __forceinline__ void xcd_barrier(const XcdBarrier& b, const int wv) {
;     ...
;             __builtin_amdgcn_fence(__ATOMIC_ACQUIRE, "agent");
;             xb_add(&bar[XB_XGEN(b.x)], 1u);
;             asm volatile("s_waitcnt vmcnt(0)" ::: "memory");
.LBB0_2078:
	s_or_b64 exec, exec, s[8:9]
	s_mov_b64 s[8:9], exec
	v_mbcnt_lo_u32_b32 v0, s8, 0
	v_mbcnt_hi_u32_b32 v0, s9, v0
	v_cmp_eq_u32_e32 vcc, 0, v0
	s_waitcnt vmcnt(0)
	buffer_inv sc1
	s_and_saveexec_b64 s[14:15], vcc
	s_cbranch_execz .LBB0_2080
	s_bcnt1_i32_b64 s3, s[8:9]
	v_mov_b32_e32 v0, 0x2000
	v_mov_b32_e32 v1, s3
.LBB0_2080:
	s_or_b64 exec, exec, s[14:15]
	s_waitcnt vmcnt(0)

; __device__ __forceinline__ unsigned xb_ld(unsigned* p)              { return __hip_atomic_load(p, __ATOMIC_RELAXED, __HIP_MEMORY_SCOPE_AGENT); }
; __device__ __forceinline__ unsigned xb_add(unsigned* p, unsigned v) { return __hip_atomic_fetch_add(p, v, __ATOMIC_RELAXED, __HIP_MEMORY_SCOPE_AGENT); }
; #define XB_SPIN(cond, bar) do { unsigned _sp = 0; while (cond) { __builtin_amdgcn_s_sleep(1); \
;     if ((++_sp & 255u) == 0u) { if (xb_ld(&(bar)[XB_TMO])) break; if (_sp > XB_SPIN_CAP) { atomicAdd(&(bar)[XB_TMO], 1u); break; } } } } while (0)
; __device__ __forceinline__ void xcd_barrier(const XcdBarrier& b, const int wv) {
;     ...
;         const unsigned old = xb_add(&bar[XB_XSUB(b.x)], 1u);
;         const unsigned gen = old / nloc;
;         if (old + 1u == (gen + 1u) * nloc) {
;             __builtin_amdgcn_fence(__ATOMIC_RELEASE, "agent");
;             asm volatile("s_waitcnt vmcnt(0)" ::: "memory");
;             const unsigned og = xb_add(&bar[XB_TOP], 1u);
;             const unsigned tg = og / nx;
;             if (og + 1u == (tg + 1u) * nx) xb_add(&bar[XB_TOPGEN], 1u);
;             else XB_SPIN(xb_ld(&bar[XB_TOPGEN]) == tg, bar);
.LBB0_2141:
	s_or_b64 exec, exec, s[14:15]
	v_cvt_f32_u32_e32 v3, v0
	s_waitcnt vmcnt(0)
	v_readfirstlane_b32 s3, v2
	s_add_u32 s14, s8, 0x7500
	s_addc_u32 s15, s9, 0
	v_rcp_iflag_f32_e32 v3, v3
	v_add_u32_e32 v1, s3, v1
	v_add_u32_e32 v4, 1, v1
	s_mov_b64 s[16:17], -1
	v_mul_f32_e32 v2, 0x4f7ffffe, v3
	v_cvt_u32_f32_e32 v2, v2
	v_sub_u32_e32 v3, 0, v0
	v_mul_lo_u32 v3, v3, v2
	v_mul_hi_u32 v3, v2, v3
	v_add_u32_e32 v2, v2, v3
	v_mul_hi_u32 v2, v1, v2
	v_mul_lo_u32 v3, v2, v0
	v_sub_u32_e32 v1, v1, v3
	v_add_u32_e32 v5, 1, v2
	v_cmp_ge_u32_e32 vcc, v1, v0
	v_sub_u32_e32 v3, v1, v0
	s_nop 0
	v_cndmask_b32_e32 v2, v2, v5, vcc
	v_cndmask_b32_e32 v1, v1, v3, vcc
	v_add_u32_e32 v3, 1, v2
	v_cmp_ge_u32_e32 vcc, v1, v0
	s_nop 1
	v_cndmask_b32_e32 v2, v2, v3, vcc
	v_mul_lo_u32 v1, v0, v2
	v_add_u32_e32 v0, v1, v0
	v_cmp_ne_u32_e32 vcc, v4, v0
	v_mov_b64_e32 v[0:1], s[14:15]
	s_cbranch_vccnz .Ldr_17
	s_add_u32 s12, s8, 0x63ff
	s_addc_u32 s13, s9, 0
	v_mov_b32_e32 v19, 1
	global_atomic_add v19, v19, s[12:13]
	global_atomic_add v19, v19, s[12:13] offset:256
	global_atomic_add v19, v19, s[12:13] offset:512
	global_atomic_add v19, v19, s[12:13] offset:768
	global_atomic_add v19, v19, s[12:13] offset:1024
	global_atomic_add v19, v19, s[12:13] offset:1280
	global_atomic_add v19, v19, s[12:13] offset:1536
	global_atomic_add v19, v19, s[12:13] offset:1792
.Ldr_17:
	s_and_saveexec_b64 s[12:13], vcc
	s_cbranch_execz .LBB0_2153
	v_mov_b32_e32 v0, 0
	global_load_dword v1, v0, s[14:15] sc1
	s_mov_b64 s[20:21], 0
	s_waitcnt vmcnt(0)
	v_cmp_eq_u32_e32 vcc, v1, v2
	s_and_saveexec_b64 s[18:19], vcc
	s_cbranch_execz .LBB0_2152
	s_add_u32 s16, s8, 0x4200
	s_addc_u32 s17, s9, 0
	s_mov_b32 s3, 1
	s_mov_b64 s[8:9], 0
	s_branch .LBB0_2145

; __device__ __forceinline__ unsigned xb_add(unsigned* p, unsigned v) { return __hip_atomic_fetch_add(p, v, __ATOMIC_RELAXED, __HIP_MEMORY_SCOPE_AGENT); }
; __device__ __forceinline__ void xcd_barrier(const XcdBarrier& b, const int wv) {
;     ...
;             __builtin_amdgcn_fence(__ATOMIC_ACQUIRE, "agent");
;             xb_add(&bar[XB_XGEN(b.x)], 1u);
;             asm volatile("s_waitcnt vmcnt(0)" ::: "memory");
.LBB0_2155:
	s_or_b64 exec, exec, s[8:9]
	s_mov_b64 s[8:9], exec
	v_mbcnt_lo_u32_b32 v0, s8, 0
	v_mbcnt_hi_u32_b32 v0, s9, v0
	v_cmp_eq_u32_e32 vcc, 0, v0
	s_waitcnt vmcnt(0)
	buffer_inv sc1
	s_and_saveexec_b64 s[12:13], vcc
	s_cbranch_execz .LBB0_2157
	s_bcnt1_i32_b64 s3, s[8:9]
	v_mov_b32_e32 v0, 0x2000
	v_mov_b32_e32 v1, s3
.LBB0_2157:
	s_or_b64 exec, exec, s[12:13]
	s_waitcnt vmcnt(0)

; __device__ __forceinline__ unsigned xb_add(unsigned* p, unsigned v) { return __hip_atomic_fetch_add(p, v, __ATOMIC_RELAXED, __HIP_MEMORY_SCOPE_AGENT); }
; __device__ __forceinline__ void xcd_barrier(const XcdBarrier& b, const int wv) {
;     ...
;             __builtin_amdgcn_fence(__ATOMIC_ACQUIRE, "agent");
;             xb_add(&bar[XB_XGEN(b.x)], 1u);
;             asm volatile("s_waitcnt vmcnt(0)" ::: "memory");
.LBB0_2240:
	s_or_b64 exec, exec, s[8:9]
	s_mov_b64 s[8:9], exec
	v_mbcnt_lo_u32_b32 v0, s8, 0
	v_mbcnt_hi_u32_b32 v0, s9, v0
	v_cmp_eq_u32_e32 vcc, 0, v0
	s_waitcnt vmcnt(0)
	buffer_inv sc1
	s_and_saveexec_b64 s[12:13], vcc
	s_cbranch_execz .LBB0_2242
	s_bcnt1_i32_b64 s3, s[8:9]
	v_mov_b32_e32 v0, 0x2000
	v_mov_b32_e32 v1, s3
.LBB0_2242:
	s_or_b64 exec, exec, s[12:13]
	s_waitcnt vmcnt(0)
